# P7/P9 epilogue: fold rstd mov into fmamk + drop dead rssp address calc; attention loops: v_pk_add_f32 split into scalar adds (bit-identical)
# baseline (speedup 1.0000x reference)
.LBB0_913:
	v_cmp_lt_i32_e32 vcc, -1, v213
	s_and_b64 s[4:5], s[14:15], vcc
	v_cndmask_b32_e64 v48, 0, 1, s[4:5]
	v_cmp_ne_u32_e32 vcc, 0, v48
	s_cbranch_vccz .LBB0_921
	v_add_u32_e32 v124, v159, v132
	v_cmp_lt_i32_e32 vcc, 62, v213
	s_xor_b64 s[52:53], s[4:5], -1
	ds_read_b128 v[112:115], v124
	ds_read_b128 v[116:119], v124 offset:32
	s_or_b64 s[16:17], vcc, s[52:53]
	v_cndmask_b32_e64 v48, 0, 1, s[16:17]
	s_and_b64 s[14:15], s[14:15], vcc
	v_cmp_ne_u32_e32 vcc, 0, v48
	s_cmp_lg_u64 vcc, exec
	s_cselect_b64 s[16:17], -1, 0
	s_or_b64 s[14:15], s[14:15], s[16:17]
	v_cndmask_b32_e64 v48, v210, 0, s[14:15]
	v_add_f32_e32 v62, v46, v48
	v_add_f32_e32 v63, v47, v48
	v_add_f32_e32 v60, v44, v48
	v_add_f32_e32 v61, v45, v48
	v_add_f32_e32 v58, v42, v48
	v_add_f32_e32 v59, v43, v48
	v_add_f32_e32 v56, v40, v48
	v_add_f32_e32 v57, v41, v48
	v_add_f32_e32 v54, v38, v48
	v_add_f32_e32 v55, v39, v48
	v_add_f32_e32 v52, v36, v48
	v_add_f32_e32 v53, v37, v48
	v_add_f32_e32 v50, v34, v48
	v_add_f32_e32 v51, v35, v48
	v_add_f32_e32 v49, v33, v48
	v_add_f32_e32 v48, v32, v48
	s_cmp_eq_u64 vcc, exec
	s_waitcnt lgkmcnt(1)
	v_mfma_f32_32x32x16_bf16 v[64:79], v[112:115], v[80:83], v[48:63]
	ds_read_b128 v[112:115], v124 offset:4608
	ds_read_b128 v[120:123], v124 offset:4640
	s_waitcnt lgkmcnt(1)
	v_mfma_f32_32x32x16_bf16 v[48:63], v[112:115], v[80:83], v[48:63]
	v_mfma_f32_32x32x16_bf16 v[64:79], v[116:119], v[84:87], v[64:79]
	ds_read_b128 v[112:115], v124 offset:64
	ds_read_b128 v[116:119], v124 offset:96
	s_waitcnt lgkmcnt(2)
	v_mfma_f32_32x32x16_bf16 v[48:63], v[120:123], v[84:87], v[48:63]
	s_waitcnt lgkmcnt(1)
	v_mfma_f32_32x32x16_bf16 v[64:79], v[112:115], v[88:91], v[64:79]
	ds_read_b128 v[112:115], v124 offset:4672
	ds_read_b128 v[214:217], v124 offset:4704
	s_waitcnt lgkmcnt(1)
	v_mfma_f32_32x32x16_bf16 v[48:63], v[112:115], v[88:91], v[48:63]
	v_mfma_f32_32x32x16_bf16 v[64:79], v[116:119], v[92:95], v[64:79]
	ds_read_b64_tr_b16 v[120:121], v160 offset:18432
	ds_read_b64_tr_b16 v[122:123], v160 offset:19968
	ds_read_b64_tr_b16 v[114:115], v160 offset:20032
	ds_read_b64_tr_b16 v[112:113], v160 offset:18496
	ds_read_b64_tr_b16 v[124:125], v160 offset:21504
	ds_read_b64_tr_b16 v[126:127], v160 offset:23040
	ds_read_b64_tr_b16 v[118:119], v160 offset:23104
	ds_read_b64_tr_b16 v[116:117], v160 offset:21568
	s_waitcnt lgkmcnt(8)
	v_mfma_f32_32x32x16_bf16 v[48:63], v[214:217], v[92:95], v[48:63]
	s_cbranch_scc1 .LBB0_918
	v_cmp_le_u32_e64 s[14:15], v161, v213
	v_cmp_le_u32_e64 s[16:17], v162, v213
	v_cmp_le_u32_e64 s[18:19], v164, v213
	v_cmp_le_u32_e64 s[20:21], v166, v213
	v_cmp_le_u32_e64 s[22:23], v168, v213
	v_cmp_le_u32_e64 s[24:25], v170, v213
	v_cmp_le_u32_e64 s[26:27], v172, v213
	v_cmp_le_u32_e64 s[28:29], v174, v213
	v_cmp_le_u32_e64 s[30:31], v176, v213
	v_cmp_le_u32_e64 s[34:35], v178, v213
	v_cmp_le_u32_e64 s[36:37], v180, v213
	v_cmp_le_u32_e64 s[38:39], v182, v213
	v_cmp_le_u32_e64 s[40:41], v184, v213
	v_cmp_le_u32_e64 s[42:43], v186, v213
	v_cmp_le_u32_e64 s[44:45], v189, v213
	s_and_b64 s[14:15], s[4:5], s[14:15]
	s_and_b64 s[16:17], s[4:5], s[16:17]
	s_and_b64 s[18:19], s[4:5], s[18:19]
	s_and_b64 s[20:21], s[4:5], s[20:21]
	s_and_b64 s[22:23], s[4:5], s[22:23]
	s_and_b64 s[24:25], s[4:5], s[24:25]
	s_and_b64 s[26:27], s[4:5], s[26:27]
	s_and_b64 s[28:29], s[4:5], s[28:29]
	s_and_b64 s[30:31], s[4:5], s[30:31]
	s_and_b64 s[34:35], s[4:5], s[34:35]
	s_and_b64 s[36:37], s[4:5], s[36:37]
	s_and_b64 s[38:39], s[4:5], s[38:39]
	s_and_b64 s[40:41], s[4:5], s[40:41]
	s_and_b64 s[42:43], s[4:5], s[42:43]
	s_and_b64 s[44:45], s[4:5], s[44:45]
	v_cmp_gt_u32_e64 s[46:47], v191, v213
	v_cmp_le_u32_e32 vcc, v138, v213
	v_cndmask_b32_e64 v48, v210, v48, s[14:15]
	v_cmp_lt_u32_e64 s[14:15], v138, v213
	v_cndmask_b32_e64 v49, v210, v49, s[16:17]
	v_cmp_le_u32_e64 s[16:17], v163, v213
	v_cndmask_b32_e64 v50, v210, v50, s[18:19]
	v_cmp_le_u32_e64 s[18:19], v165, v213
	v_cndmask_b32_e64 v51, v210, v51, s[20:21]
	v_cmp_le_u32_e64 s[20:21], v167, v213
	v_cndmask_b32_e64 v52, v210, v52, s[22:23]
	v_cmp_le_u32_e64 s[22:23], v169, v213
	v_cndmask_b32_e64 v53, v210, v53, s[24:25]
	v_cmp_le_u32_e64 s[24:25], v171, v213
	v_cndmask_b32_e64 v54, v210, v54, s[26:27]
	v_cmp_le_u32_e64 s[26:27], v173, v213
	v_cndmask_b32_e64 v55, v210, v55, s[28:29]
	v_cmp_le_u32_e64 s[28:29], v175, v213
	v_cndmask_b32_e64 v56, v210, v56, s[30:31]
	v_cmp_le_u32_e64 s[30:31], v177, v213
	v_cndmask_b32_e64 v57, v210, v57, s[34:35]
	v_cmp_le_u32_e64 s[34:35], v179, v213
	v_cndmask_b32_e64 v58, v210, v58, s[36:37]
	v_cmp_le_u32_e64 s[36:37], v181, v213
	v_cndmask_b32_e64 v59, v210, v59, s[38:39]
	v_cmp_le_u32_e64 s[38:39], v183, v213
	v_cndmask_b32_e64 v60, v210, v60, s[40:41]
	v_cmp_le_u32_e64 s[40:41], v185, v213
	v_cndmask_b32_e64 v61, v210, v61, s[42:43]
	v_cmp_le_u32_e64 s[42:43], v187, v213
	v_cndmask_b32_e64 v62, v210, v62, s[44:45]
	v_cmp_le_u32_e64 s[44:45], v190, v213
	s_or_b64 s[52:53], s[52:53], s[46:47]
	s_and_saveexec_b64 s[46:47], s[52:53]
	v_mov_b32_e32 v63, s33
	s_or_b64 exec, exec, s[46:47]
	s_and_b64 vcc, s[4:5], vcc
	v_cndmask_b32_e32 v64, v210, v64, vcc
	s_and_b64 vcc, s[4:5], s[14:15]
	v_cndmask_b32_e32 v65, v210, v65, vcc
	s_and_b64 vcc, s[4:5], s[16:17]
	v_cndmask_b32_e32 v66, v210, v66, vcc
	s_and_b64 vcc, s[4:5], s[18:19]
	v_cndmask_b32_e32 v67, v210, v67, vcc
	s_and_b64 vcc, s[4:5], s[20:21]
	v_cndmask_b32_e32 v68, v210, v68, vcc
	s_and_b64 vcc, s[4:5], s[22:23]
	v_cndmask_b32_e32 v69, v210, v69, vcc
	s_and_b64 vcc, s[4:5], s[24:25]
	v_cndmask_b32_e32 v70, v210, v70, vcc
	s_and_b64 vcc, s[4:5], s[26:27]
	v_cndmask_b32_e32 v71, v210, v71, vcc
	s_and_b64 vcc, s[4:5], s[28:29]
	v_cndmask_b32_e32 v72, v210, v72, vcc
	s_and_b64 vcc, s[4:5], s[30:31]
	v_cndmask_b32_e32 v73, v210, v73, vcc
	s_and_b64 vcc, s[4:5], s[34:35]
	v_cndmask_b32_e32 v74, v210, v74, vcc
	s_and_b64 vcc, s[4:5], s[36:37]
	v_cndmask_b32_e32 v75, v210, v75, vcc
	s_and_b64 vcc, s[4:5], s[38:39]
	v_cndmask_b32_e32 v76, v210, v76, vcc
	s_and_b64 vcc, s[4:5], s[40:41]
	v_cndmask_b32_e32 v77, v210, v77, vcc
	s_and_b64 vcc, s[4:5], s[42:43]
	v_cndmask_b32_e32 v78, v210, v78, vcc
	s_and_b64 vcc, s[4:5], s[44:45]
	v_cndmask_b32_e32 v79, v210, v79, vcc

.LBB0_920:
	v_exp_f32_e32 v215, v64
	v_exp_f32_e32 v214, v48
	v_exp_f32_e32 v217, v65
	v_exp_f32_e32 v216, v49
	v_exp_f32_e32 v219, v66
	v_exp_f32_e32 v218, v50
	v_exp_f32_e32 v221, v67
	v_exp_f32_e32 v225, v68
	v_exp_f32_e32 v69, v69
	v_exp_f32_e32 v227, v70
	v_exp_f32_e32 v71, v71
	v_mov_b32_e32 v48, v214
	v_mov_b32_e32 v49, v215
	v_exp_f32_e32 v220, v51
	v_add_f32_e32 v48, v216, v48
	v_add_f32_e32 v49, v217, v49
	v_cvt_pk_bf16_f32 v50, v225, v69
	v_add_f32_e32 v222, v218, v48
	v_add_f32_e32 v223, v219, v49
	v_cvt_pk_bf16_f32 v48, v215, v217
	v_cvt_pk_bf16_f32 v49, v219, v221
	v_cvt_pk_bf16_f32 v51, v227, v71
	v_exp_f32_e32 v229, v72
	v_exp_f32_e32 v73, v73
	s_waitcnt lgkmcnt(6)
	v_mfma_f32_32x32x16_bf16 v[0:15], v[120:123], v[48:51], v[0:15]
	v_exp_f32_e32 v231, v74
	v_exp_f32_e32 v75, v75
	v_exp_f32_e32 v233, v76
	v_exp_f32_e32 v77, v77
	v_exp_f32_e32 v121, v78
	v_exp_f32_e32 v79, v79
	v_cvt_pk_bf16_f32 v64, v229, v73
	s_waitcnt lgkmcnt(4)
	v_mfma_f32_32x32x16_bf16 v[16:31], v[112:115], v[48:51], v[16:31]
	v_cvt_pk_bf16_f32 v65, v231, v75
	v_cvt_pk_bf16_f32 v66, v233, v77
	v_cvt_pk_bf16_f32 v67, v121, v79
	v_exp_f32_e32 v224, v52
	v_exp_f32_e32 v68, v53
	v_exp_f32_e32 v226, v54
	v_exp_f32_e32 v70, v55
	s_waitcnt lgkmcnt(2)
	v_mfma_f32_32x32x16_bf16 v[0:15], v[124:127], v[64:67], v[0:15]
	ds_read_b64_tr_b16 v[48:49], v160 offset:24576
	ds_read_b64_tr_b16 v[50:51], v160 offset:26112
	v_exp_f32_e32 v228, v56
	v_exp_f32_e32 v72, v57
	v_exp_f32_e32 v230, v58
	v_exp_f32_e32 v74, v59
	ds_read_b64_tr_b16 v[52:53], v160 offset:27648
	ds_read_b64_tr_b16 v[54:55], v160 offset:29184
	ds_read_b64_tr_b16 v[58:59], v160 offset:26176
	ds_read_b64_tr_b16 v[56:57], v160 offset:24640
	v_exp_f32_e32 v232, v60
	s_waitcnt lgkmcnt(6)
	v_mfma_f32_32x32x16_bf16 v[16:31], v[116:119], v[64:67], v[16:31]
	v_cvt_pk_bf16_f32 v64, v214, v216
	v_cvt_pk_bf16_f32 v65, v218, v220
	v_cvt_pk_bf16_f32 v66, v224, v68
	v_cvt_pk_bf16_f32 v67, v226, v70
	v_exp_f32_e32 v76, v61
	v_exp_f32_e32 v120, v62
	v_exp_f32_e32 v78, v63
	s_waitcnt lgkmcnt(4)
	v_mfma_f32_32x32x16_bf16 v[0:15], v[48:51], v[64:67], v[0:15]
	v_add_f32_e64 v122, v220, v222
	v_add_f32_e64 v123, v221, v223
	v_cvt_pk_bf16_f32 v60, v228, v72
	v_cvt_pk_bf16_f32 v61, v230, v74
	v_cvt_pk_bf16_f32 v62, v232, v76
	v_cvt_pk_bf16_f32 v63, v120, v78
	ds_read_b64_tr_b16 v[50:51], v160 offset:29248
	ds_read_b64_tr_b16 v[48:49], v160 offset:27712
	s_waitcnt lgkmcnt(2)
	v_mfma_f32_32x32x16_bf16 v[16:31], v[56:59], v[64:67], v[16:31]
	v_mfma_f32_32x32x16_bf16 v[0:15], v[52:55], v[60:63], v[0:15]
	v_add_f32_e64 v52, v224, v122
	v_add_f32_e64 v53, v225, v123
	v_add_f32_e64 v52, v68, v52
	v_add_f32_e64 v53, v69, v53
	v_add_f32_e64 v52, v226, v52
	v_add_f32_e64 v53, v227, v53
	v_add_f32_e32 v52, v70, v52
	v_add_f32_e32 v53, v71, v53
	s_waitcnt lgkmcnt(0)
	v_mfma_f32_32x32x16_bf16 v[16:31], v[48:51], v[60:63], v[16:31]
	v_add_f32_e64 v52, v228, v52
	v_add_f32_e64 v53, v229, v53
	v_add_f32_e64 v52, v72, v52
	v_add_f32_e64 v53, v73, v53
	v_add_f32_e64 v52, v230, v52
	v_add_f32_e64 v53, v231, v53
	v_add_f32_e32 v52, v74, v52
	v_add_f32_e32 v53, v75, v53
	v_add_f32_e32 v52, v232, v52
	v_add_f32_e32 v53, v233, v53
	v_add_f32_e32 v52, v76, v52
	v_add_f32_e32 v53, v77, v53
	v_add_f32_e32 v52, v120, v52
	v_add_f32_e32 v53, v121, v53
	v_add_f32_e32 v52, v78, v52
	v_add_f32_e32 v53, v79, v53
	v_add_f32_e32 v52, v52, v53
	v_add_f32_e32 v147, v147, v52

.LBB0_928:
	v_cmp_lt_i32_e32 vcc, -1, v149
	s_and_b64 s[4:5], s[14:15], vcc
	v_cndmask_b32_e64 v48, 0, 1, s[4:5]
	v_cmp_ne_u32_e32 vcc, 0, v48
	s_cbranch_vccz .LBB0_936
	v_add_u32_e32 v124, v159, v132
	v_cmp_lt_i32_e32 vcc, 62, v149
	s_xor_b64 s[50:51], s[4:5], -1
	ds_read_b128 v[112:115], v124 offset:9216
	ds_read_b128 v[116:119], v124 offset:9248
	s_or_b64 s[16:17], vcc, s[50:51]
	v_cndmask_b32_e64 v48, 0, 1, s[16:17]
	s_and_b64 s[14:15], s[14:15], vcc
	v_cmp_ne_u32_e32 vcc, 0, v48
	s_cmp_lg_u64 vcc, exec
	s_cselect_b64 s[16:17], -1, 0
	s_or_b64 s[14:15], s[14:15], s[16:17]
	v_cndmask_b32_e64 v48, v210, 0, s[14:15]
	v_add_f32_e32 v62, v46, v48
	v_add_f32_e32 v63, v47, v48
	v_add_f32_e32 v60, v44, v48
	v_add_f32_e32 v61, v45, v48
	v_add_f32_e32 v58, v42, v48
	v_add_f32_e32 v59, v43, v48
	v_add_f32_e32 v56, v40, v48
	v_add_f32_e32 v57, v41, v48
	v_add_f32_e32 v54, v38, v48
	v_add_f32_e32 v55, v39, v48
	v_add_f32_e32 v52, v36, v48
	v_add_f32_e32 v53, v37, v48
	v_add_f32_e32 v50, v34, v48
	v_add_f32_e32 v51, v35, v48
	v_add_f32_e32 v49, v33, v48
	v_add_f32_e32 v48, v32, v48
	s_cmp_eq_u64 vcc, exec
	s_waitcnt lgkmcnt(1)
	v_mfma_f32_32x32x16_bf16 v[64:79], v[112:115], v[80:83], v[48:63]
	ds_read_b128 v[112:115], v124 offset:13824
	ds_read_b128 v[120:123], v124 offset:13856
	s_waitcnt lgkmcnt(1)
	v_mfma_f32_32x32x16_bf16 v[48:63], v[112:115], v[80:83], v[48:63]
	v_mfma_f32_32x32x16_bf16 v[64:79], v[116:119], v[84:87], v[64:79]
	ds_read_b128 v[112:115], v124 offset:9280
	ds_read_b128 v[116:119], v124 offset:9312
	s_waitcnt lgkmcnt(2)
	v_mfma_f32_32x32x16_bf16 v[48:63], v[120:123], v[84:87], v[48:63]
	s_waitcnt lgkmcnt(1)
	v_mfma_f32_32x32x16_bf16 v[64:79], v[112:115], v[88:91], v[64:79]
	ds_read_b128 v[112:115], v124 offset:13888
	ds_read_b128 v[212:215], v124 offset:13920
	s_waitcnt lgkmcnt(1)
	v_mfma_f32_32x32x16_bf16 v[48:63], v[112:115], v[88:91], v[48:63]
	v_mfma_f32_32x32x16_bf16 v[64:79], v[116:119], v[92:95], v[64:79]
	ds_read_b64_tr_b16 v[120:121], v160 offset:30720
	ds_read_b64_tr_b16 v[122:123], v160 offset:32256
	ds_read_b64_tr_b16 v[114:115], v160 offset:32320
	ds_read_b64_tr_b16 v[112:113], v160 offset:30784
	ds_read_b64_tr_b16 v[124:125], v160 offset:33792
	ds_read_b64_tr_b16 v[126:127], v160 offset:35328
	ds_read_b64_tr_b16 v[118:119], v160 offset:35392
	ds_read_b64_tr_b16 v[116:117], v160 offset:33856
	s_waitcnt lgkmcnt(8)
	v_mfma_f32_32x32x16_bf16 v[48:63], v[212:215], v[92:95], v[48:63]
	s_cbranch_scc1 .LBB0_933
	v_cmp_le_u32_e64 s[14:15], v161, v149
	v_cmp_le_u32_e64 s[16:17], v162, v149
	v_cmp_le_u32_e64 s[18:19], v164, v149
	v_cmp_le_u32_e64 s[20:21], v166, v149
	v_cmp_le_u32_e64 s[22:23], v168, v149
	v_cmp_le_u32_e64 s[24:25], v170, v149
	v_cmp_le_u32_e64 s[26:27], v172, v149
	v_cmp_le_u32_e64 s[28:29], v174, v149
	v_cmp_le_u32_e64 s[30:31], v176, v149
	v_cmp_le_u32_e64 s[34:35], v178, v149
	v_cmp_le_u32_e64 s[36:37], v180, v149
	v_cmp_le_u32_e64 s[38:39], v182, v149
	v_cmp_le_u32_e64 s[40:41], v184, v149
	v_cmp_le_u32_e64 s[42:43], v186, v149
	v_cmp_le_u32_e64 s[44:45], v189, v149
	s_and_b64 s[14:15], s[4:5], s[14:15]
	s_and_b64 s[16:17], s[4:5], s[16:17]
	s_and_b64 s[18:19], s[4:5], s[18:19]
	s_and_b64 s[20:21], s[4:5], s[20:21]
	s_and_b64 s[22:23], s[4:5], s[22:23]
	s_and_b64 s[24:25], s[4:5], s[24:25]
	s_and_b64 s[26:27], s[4:5], s[26:27]
	s_and_b64 s[28:29], s[4:5], s[28:29]
	s_and_b64 s[30:31], s[4:5], s[30:31]
	s_and_b64 s[34:35], s[4:5], s[34:35]
	s_and_b64 s[36:37], s[4:5], s[36:37]
	s_and_b64 s[38:39], s[4:5], s[38:39]
	s_and_b64 s[40:41], s[4:5], s[40:41]
	s_and_b64 s[42:43], s[4:5], s[42:43]
	s_and_b64 s[44:45], s[4:5], s[44:45]
	v_cmp_gt_u32_e64 s[46:47], v191, v149
	v_cmp_le_u32_e32 vcc, v138, v149
	v_cndmask_b32_e64 v48, v210, v48, s[14:15]
	v_cmp_lt_u32_e64 s[14:15], v138, v149
	v_cndmask_b32_e64 v49, v210, v49, s[16:17]
	v_cmp_le_u32_e64 s[16:17], v163, v149
	v_cndmask_b32_e64 v50, v210, v50, s[18:19]
	v_cmp_le_u32_e64 s[18:19], v165, v149
	v_cndmask_b32_e64 v51, v210, v51, s[20:21]
	v_cmp_le_u32_e64 s[20:21], v167, v149
	v_cndmask_b32_e64 v52, v210, v52, s[22:23]
	v_cmp_le_u32_e64 s[22:23], v169, v149
	v_cndmask_b32_e64 v53, v210, v53, s[24:25]
	v_cmp_le_u32_e64 s[24:25], v171, v149
	v_cndmask_b32_e64 v54, v210, v54, s[26:27]
	v_cmp_le_u32_e64 s[26:27], v173, v149
	v_cndmask_b32_e64 v55, v210, v55, s[28:29]
	v_cmp_le_u32_e64 s[28:29], v175, v149
	v_cndmask_b32_e64 v56, v210, v56, s[30:31]
	v_cmp_le_u32_e64 s[30:31], v177, v149
	v_cndmask_b32_e64 v57, v210, v57, s[34:35]
	v_cmp_le_u32_e64 s[34:35], v179, v149
	v_cndmask_b32_e64 v58, v210, v58, s[36:37]
	v_cmp_le_u32_e64 s[36:37], v181, v149
	v_cndmask_b32_e64 v59, v210, v59, s[38:39]
	v_cmp_le_u32_e64 s[38:39], v183, v149
	v_cndmask_b32_e64 v60, v210, v60, s[40:41]
	v_cmp_le_u32_e64 s[40:41], v185, v149
	v_cndmask_b32_e64 v61, v210, v61, s[42:43]
	v_cmp_le_u32_e64 s[42:43], v187, v149
	v_cndmask_b32_e64 v62, v210, v62, s[44:45]
	v_cmp_le_u32_e64 s[44:45], v190, v149
	s_or_b64 s[50:51], s[50:51], s[46:47]
	s_and_saveexec_b64 s[46:47], s[50:51]
	v_mov_b32_e32 v63, s33
	s_or_b64 exec, exec, s[46:47]
	s_and_b64 vcc, s[4:5], vcc
	v_cndmask_b32_e32 v64, v210, v64, vcc
	s_and_b64 vcc, s[4:5], s[14:15]
	v_cndmask_b32_e32 v65, v210, v65, vcc
	s_and_b64 vcc, s[4:5], s[16:17]
	v_cndmask_b32_e32 v66, v210, v66, vcc
	s_and_b64 vcc, s[4:5], s[18:19]
	v_cndmask_b32_e32 v67, v210, v67, vcc
	s_and_b64 vcc, s[4:5], s[20:21]
	v_cndmask_b32_e32 v68, v210, v68, vcc
	s_and_b64 vcc, s[4:5], s[22:23]
	v_cndmask_b32_e32 v69, v210, v69, vcc
	s_and_b64 vcc, s[4:5], s[24:25]
	v_cndmask_b32_e32 v70, v210, v70, vcc
	s_and_b64 vcc, s[4:5], s[26:27]
	v_cndmask_b32_e32 v71, v210, v71, vcc
	s_and_b64 vcc, s[4:5], s[28:29]
	v_cndmask_b32_e32 v72, v210, v72, vcc
	s_and_b64 vcc, s[4:5], s[30:31]
	v_cndmask_b32_e32 v73, v210, v73, vcc
	s_and_b64 vcc, s[4:5], s[34:35]
	v_cndmask_b32_e32 v74, v210, v74, vcc
	s_and_b64 vcc, s[4:5], s[36:37]
	v_cndmask_b32_e32 v75, v210, v75, vcc
	s_and_b64 vcc, s[4:5], s[38:39]
	v_cndmask_b32_e32 v76, v210, v76, vcc
	s_and_b64 vcc, s[4:5], s[40:41]
	v_cndmask_b32_e32 v77, v210, v77, vcc
	s_and_b64 vcc, s[4:5], s[42:43]
	v_cndmask_b32_e32 v78, v210, v78, vcc
	s_and_b64 vcc, s[4:5], s[44:45]
	v_cndmask_b32_e32 v79, v210, v79, vcc

.LBB0_935:
	v_exp_f32_e32 v213, v64
	v_exp_f32_e32 v212, v48
	v_exp_f32_e32 v215, v65
	v_exp_f32_e32 v214, v49
	v_exp_f32_e32 v217, v66
	v_exp_f32_e32 v216, v50
	v_exp_f32_e32 v219, v67
	v_exp_f32_e32 v223, v68
	v_exp_f32_e32 v69, v69
	v_exp_f32_e32 v225, v70
	v_exp_f32_e32 v71, v71
	v_mov_b32_e32 v48, v212
	v_mov_b32_e32 v49, v213
	v_exp_f32_e32 v218, v51
	v_add_f32_e32 v48, v214, v48
	v_add_f32_e32 v49, v215, v49
	v_cvt_pk_bf16_f32 v50, v223, v69
	v_add_f32_e32 v220, v216, v48
	v_add_f32_e32 v221, v217, v49
	v_cvt_pk_bf16_f32 v48, v213, v215
	v_cvt_pk_bf16_f32 v49, v217, v219
	v_cvt_pk_bf16_f32 v51, v225, v71
	v_exp_f32_e32 v227, v72
	v_exp_f32_e32 v73, v73
	s_waitcnt lgkmcnt(6)
	v_mfma_f32_32x32x16_bf16 v[0:15], v[120:123], v[48:51], v[0:15]
	v_exp_f32_e32 v229, v74
	v_exp_f32_e32 v75, v75
	v_exp_f32_e32 v231, v76
	v_exp_f32_e32 v77, v77
	v_exp_f32_e32 v121, v78
	v_exp_f32_e32 v79, v79
	v_cvt_pk_bf16_f32 v64, v227, v73
	s_waitcnt lgkmcnt(4)
	v_mfma_f32_32x32x16_bf16 v[16:31], v[112:115], v[48:51], v[16:31]
	v_cvt_pk_bf16_f32 v65, v229, v75
	v_cvt_pk_bf16_f32 v66, v231, v77
	v_cvt_pk_bf16_f32 v67, v121, v79
	v_exp_f32_e32 v222, v52
	v_exp_f32_e32 v68, v53
	v_exp_f32_e32 v224, v54
	v_exp_f32_e32 v70, v55
	s_waitcnt lgkmcnt(2)
	v_mfma_f32_32x32x16_bf16 v[0:15], v[124:127], v[64:67], v[0:15]
	ds_read_b64_tr_b16 v[48:49], v160 offset:36864
	ds_read_b64_tr_b16 v[50:51], v160 offset:38400
	v_exp_f32_e32 v226, v56
	v_exp_f32_e32 v72, v57
	v_exp_f32_e32 v228, v58
	v_exp_f32_e32 v74, v59
	ds_read_b64_tr_b16 v[52:53], v160 offset:39936
	ds_read_b64_tr_b16 v[54:55], v160 offset:41472
	ds_read_b64_tr_b16 v[58:59], v160 offset:38464
	ds_read_b64_tr_b16 v[56:57], v160 offset:36928
	v_exp_f32_e32 v230, v60
	s_waitcnt lgkmcnt(6)
	v_mfma_f32_32x32x16_bf16 v[16:31], v[116:119], v[64:67], v[16:31]
	v_cvt_pk_bf16_f32 v64, v212, v214
	v_cvt_pk_bf16_f32 v65, v216, v218
	v_cvt_pk_bf16_f32 v66, v222, v68
	v_cvt_pk_bf16_f32 v67, v224, v70
	v_exp_f32_e32 v76, v61
	v_exp_f32_e32 v120, v62
	v_exp_f32_e32 v78, v63
	s_waitcnt lgkmcnt(4)
	v_mfma_f32_32x32x16_bf16 v[0:15], v[48:51], v[64:67], v[0:15]
	v_add_f32_e64 v122, v218, v220
	v_add_f32_e64 v123, v219, v221
	v_cvt_pk_bf16_f32 v60, v226, v72
	v_cvt_pk_bf16_f32 v61, v228, v74
	v_cvt_pk_bf16_f32 v62, v230, v76
	v_cvt_pk_bf16_f32 v63, v120, v78
	ds_read_b64_tr_b16 v[50:51], v160 offset:41536
	ds_read_b64_tr_b16 v[48:49], v160 offset:40000
	s_waitcnt lgkmcnt(2)
	v_mfma_f32_32x32x16_bf16 v[16:31], v[56:59], v[64:67], v[16:31]
	v_mfma_f32_32x32x16_bf16 v[0:15], v[52:55], v[60:63], v[0:15]
	v_add_f32_e64 v52, v222, v122
	v_add_f32_e64 v53, v223, v123
	v_add_f32_e64 v52, v68, v52
	v_add_f32_e64 v53, v69, v53
	v_add_f32_e64 v52, v224, v52
	v_add_f32_e64 v53, v225, v53
	v_add_f32_e32 v52, v70, v52
	v_add_f32_e32 v53, v71, v53
	s_waitcnt lgkmcnt(0)
	v_mfma_f32_32x32x16_bf16 v[16:31], v[48:51], v[60:63], v[16:31]
	v_add_f32_e64 v52, v226, v52
	v_add_f32_e64 v53, v227, v53
	v_add_f32_e64 v52, v72, v52
	v_add_f32_e64 v53, v73, v53
	v_add_f32_e64 v52, v228, v52
	v_add_f32_e64 v53, v229, v53
	v_add_f32_e32 v52, v74, v52
	v_add_f32_e32 v53, v75, v53
	v_add_f32_e32 v52, v230, v52
	v_add_f32_e32 v53, v231, v53
	v_add_f32_e32 v52, v76, v52
	v_add_f32_e32 v53, v77, v53
	v_add_f32_e32 v52, v120, v52
	v_add_f32_e32 v53, v121, v53
	v_add_f32_e32 v52, v78, v52
	v_add_f32_e32 v53, v79, v53
	v_add_f32_e32 v52, v52, v53
	v_add_f32_e32 v147, v147, v52

.Lme_fast:
	v_lshrrev_b32_e32 v48, s54, v146
	v_and_b32_e32 v48, 1, v48
	v_cmp_eq_u32_e32 vcc, 1, v48
	s_cbranch_vccz .LBB0_921
	v_add_u32_e32 v124, v159, v132
	s_nop 0
	v_cndmask_b32_e64 v48, v210, 0, vcc
	v_add_f32_e32 v62, v46, v48
	v_add_f32_e32 v63, v47, v48
	v_add_f32_e32 v60, v44, v48
	v_add_f32_e32 v61, v45, v48
	v_add_f32_e32 v58, v42, v48
	v_add_f32_e32 v59, v43, v48
	v_add_f32_e32 v56, v40, v48
	v_add_f32_e32 v57, v41, v48
	v_add_f32_e32 v54, v38, v48
	v_add_f32_e32 v55, v39, v48
	v_add_f32_e32 v52, v36, v48
	v_add_f32_e32 v53, v37, v48
	v_add_f32_e32 v50, v34, v48
	v_add_f32_e32 v51, v35, v48
	v_add_f32_e32 v49, v33, v48
	v_add_f32_e32 v48, v32, v48
	ds_read_b128 v[112:115], v124
	ds_read_b128 v[116:119], v124 offset:32
	s_waitcnt lgkmcnt(1)
	v_mfma_f32_32x32x16_bf16 v[64:79], v[112:115], v[80:83], v[48:63]
	ds_read_b128 v[112:115], v124 offset:4608
	ds_read_b128 v[120:123], v124 offset:4640
	s_waitcnt lgkmcnt(1)
	v_mfma_f32_32x32x16_bf16 v[48:63], v[112:115], v[80:83], v[48:63]
	v_mfma_f32_32x32x16_bf16 v[64:79], v[116:119], v[84:87], v[64:79]
	ds_read_b128 v[112:115], v124 offset:64
	ds_read_b128 v[116:119], v124 offset:96
	s_waitcnt lgkmcnt(2)
	v_mfma_f32_32x32x16_bf16 v[48:63], v[120:123], v[84:87], v[48:63]
	s_waitcnt lgkmcnt(1)
	v_mfma_f32_32x32x16_bf16 v[64:79], v[112:115], v[88:91], v[64:79]
	ds_read_b128 v[112:115], v124 offset:4672
	ds_read_b128 v[214:217], v124 offset:4704
	s_waitcnt lgkmcnt(1)
	v_mfma_f32_32x32x16_bf16 v[48:63], v[112:115], v[88:91], v[48:63]
	v_mfma_f32_32x32x16_bf16 v[64:79], v[116:119], v[92:95], v[64:79]
	ds_read_b64_tr_b16 v[120:121], v160 offset:18432
	ds_read_b64_tr_b16 v[122:123], v160 offset:19968
	ds_read_b64_tr_b16 v[114:115], v160 offset:20032
	ds_read_b64_tr_b16 v[112:113], v160 offset:18496
	ds_read_b64_tr_b16 v[124:125], v160 offset:21504
	ds_read_b64_tr_b16 v[126:127], v160 offset:23040
	ds_read_b64_tr_b16 v[118:119], v160 offset:23104
	ds_read_b64_tr_b16 v[116:117], v160 offset:21568
	s_waitcnt lgkmcnt(8)
	v_mfma_f32_32x32x16_bf16 v[48:63], v[214:217], v[92:95], v[48:63]
	s_branch .LBB0_918
.Lmo_fast:
	v_lshrrev_b32_e32 v48, s54, v146
	v_and_b32_e32 v48, 1, v48
	v_cmp_eq_u32_e32 vcc, 1, v48
	s_cbranch_vccz .LBB0_936
	v_add_u32_e32 v124, v159, v132
	s_nop 0
	v_cndmask_b32_e64 v48, v210, 0, vcc
	v_add_f32_e32 v62, v46, v48
	v_add_f32_e32 v63, v47, v48
	v_add_f32_e32 v60, v44, v48
	v_add_f32_e32 v61, v45, v48
	v_add_f32_e32 v58, v42, v48
	v_add_f32_e32 v59, v43, v48
	v_add_f32_e32 v56, v40, v48
	v_add_f32_e32 v57, v41, v48
	v_add_f32_e32 v54, v38, v48
	v_add_f32_e32 v55, v39, v48
	v_add_f32_e32 v52, v36, v48
	v_add_f32_e32 v53, v37, v48
	v_add_f32_e32 v50, v34, v48
	v_add_f32_e32 v51, v35, v48
	v_add_f32_e32 v49, v33, v48
	v_add_f32_e32 v48, v32, v48
	ds_read_b128 v[112:115], v124 offset:9216
	ds_read_b128 v[116:119], v124 offset:9248
	s_waitcnt lgkmcnt(1)
	v_mfma_f32_32x32x16_bf16 v[64:79], v[112:115], v[80:83], v[48:63]
	ds_read_b128 v[112:115], v124 offset:13824
	ds_read_b128 v[120:123], v124 offset:13856
	s_waitcnt lgkmcnt(1)
	v_mfma_f32_32x32x16_bf16 v[48:63], v[112:115], v[80:83], v[48:63]
	v_mfma_f32_32x32x16_bf16 v[64:79], v[116:119], v[84:87], v[64:79]
	ds_read_b128 v[112:115], v124 offset:9280
	ds_read_b128 v[116:119], v124 offset:9312
	s_waitcnt lgkmcnt(2)
	v_mfma_f32_32x32x16_bf16 v[48:63], v[120:123], v[84:87], v[48:63]
	s_waitcnt lgkmcnt(1)
	v_mfma_f32_32x32x16_bf16 v[64:79], v[112:115], v[88:91], v[64:79]
	ds_read_b128 v[112:115], v124 offset:13888
	ds_read_b128 v[212:215], v124 offset:13920
	s_waitcnt lgkmcnt(1)
	v_mfma_f32_32x32x16_bf16 v[48:63], v[112:115], v[88:91], v[48:63]
	v_mfma_f32_32x32x16_bf16 v[64:79], v[116:119], v[92:95], v[64:79]
	ds_read_b64_tr_b16 v[120:121], v160 offset:30720
	ds_read_b64_tr_b16 v[122:123], v160 offset:32256
	ds_read_b64_tr_b16 v[114:115], v160 offset:32320
	ds_read_b64_tr_b16 v[112:113], v160 offset:30784
	ds_read_b64_tr_b16 v[124:125], v160 offset:33792
	ds_read_b64_tr_b16 v[126:127], v160 offset:35328
	ds_read_b64_tr_b16 v[118:119], v160 offset:35392
	ds_read_b64_tr_b16 v[116:117], v160 offset:33856
	s_waitcnt lgkmcnt(8)
	v_mfma_f32_32x32x16_bf16 v[48:63], v[212:215], v[92:95], v[48:63]
	s_branch .LBB0_933

.LBB0_1011:
	v_exp_f32_e32 v217, v64
	v_exp_f32_e32 v216, v48
	v_exp_f32_e32 v219, v65
	v_exp_f32_e32 v218, v49
	v_exp_f32_e32 v221, v66
	v_exp_f32_e32 v220, v50
	v_exp_f32_e32 v223, v67
	v_exp_f32_e32 v227, v68
	v_exp_f32_e32 v69, v69
	v_exp_f32_e32 v229, v70
	v_exp_f32_e32 v71, v71
	v_mov_b32_e32 v48, v216
	v_mov_b32_e32 v49, v217
	v_exp_f32_e32 v222, v51
	v_add_f32_e32 v48, v218, v48
	v_add_f32_e32 v49, v219, v49
	v_cvt_pk_bf16_f32 v50, v227, v69
	v_add_f32_e32 v224, v220, v48
	v_add_f32_e32 v225, v221, v49
	v_cvt_pk_bf16_f32 v48, v217, v219
	v_cvt_pk_bf16_f32 v49, v221, v223
	v_cvt_pk_bf16_f32 v51, v229, v71
	v_exp_f32_e32 v231, v72
	v_exp_f32_e32 v73, v73
	s_waitcnt lgkmcnt(6)
	v_mfma_f32_32x32x16_bf16 v[16:31], v[120:123], v[48:51], v[16:31]
	v_exp_f32_e32 v233, v74
	v_exp_f32_e32 v75, v75
	v_exp_f32_e32 v235, v76
	v_exp_f32_e32 v77, v77
	v_exp_f32_e32 v121, v78
	v_exp_f32_e32 v79, v79
	v_cvt_pk_bf16_f32 v64, v231, v73
	s_waitcnt lgkmcnt(4)
	v_mfma_f32_32x32x16_bf16 v[0:15], v[112:115], v[48:51], v[0:15]
	v_cvt_pk_bf16_f32 v65, v233, v75
	v_cvt_pk_bf16_f32 v66, v235, v77
	v_cvt_pk_bf16_f32 v67, v121, v79
	v_exp_f32_e32 v226, v52
	v_exp_f32_e32 v68, v53
	v_exp_f32_e32 v228, v54
	v_exp_f32_e32 v70, v55
	s_waitcnt lgkmcnt(2)
	v_mfma_f32_32x32x16_bf16 v[16:31], v[124:127], v[64:67], v[16:31]
	ds_read_b64_tr_b16 v[48:49], v160 offset:36864
	ds_read_b64_tr_b16 v[50:51], v160 offset:38400
	v_exp_f32_e32 v230, v56
	v_exp_f32_e32 v72, v57
	v_exp_f32_e32 v232, v58
	v_exp_f32_e32 v74, v59
	ds_read_b64_tr_b16 v[52:53], v160 offset:39936
	ds_read_b64_tr_b16 v[54:55], v160 offset:41472
	ds_read_b64_tr_b16 v[58:59], v160 offset:38464
	ds_read_b64_tr_b16 v[56:57], v160 offset:36928
	v_exp_f32_e32 v234, v60
	s_waitcnt lgkmcnt(6)
	v_mfma_f32_32x32x16_bf16 v[0:15], v[116:119], v[64:67], v[0:15]
	v_cvt_pk_bf16_f32 v64, v216, v218
	v_cvt_pk_bf16_f32 v65, v220, v222
	v_cvt_pk_bf16_f32 v66, v226, v68
	v_cvt_pk_bf16_f32 v67, v228, v70
	v_exp_f32_e32 v76, v61
	v_exp_f32_e32 v120, v62
	v_exp_f32_e32 v78, v63
	s_waitcnt lgkmcnt(4)
	v_mfma_f32_32x32x16_bf16 v[16:31], v[48:51], v[64:67], v[16:31]
	v_add_f32_e64 v122, v222, v224
	v_add_f32_e64 v123, v223, v225
	v_cvt_pk_bf16_f32 v60, v230, v72
	v_cvt_pk_bf16_f32 v61, v232, v74
	v_cvt_pk_bf16_f32 v62, v234, v76
	v_cvt_pk_bf16_f32 v63, v120, v78
	ds_read_b64_tr_b16 v[50:51], v160 offset:41536
	ds_read_b64_tr_b16 v[48:49], v160 offset:40000
	s_waitcnt lgkmcnt(2)
	v_mfma_f32_32x32x16_bf16 v[0:15], v[56:59], v[64:67], v[0:15]
	v_mfma_f32_32x32x16_bf16 v[16:31], v[52:55], v[60:63], v[16:31]
	v_add_f32_e64 v52, v226, v122
	v_add_f32_e64 v53, v227, v123
	v_add_f32_e64 v52, v68, v52
	v_add_f32_e64 v53, v69, v53
	v_add_f32_e64 v52, v228, v52
	v_add_f32_e64 v53, v229, v53
	v_add_f32_e32 v52, v70, v52
	v_add_f32_e32 v53, v71, v53
	s_waitcnt lgkmcnt(0)
	v_mfma_f32_32x32x16_bf16 v[0:15], v[48:51], v[60:63], v[0:15]
	v_add_f32_e64 v52, v230, v52
	v_add_f32_e64 v53, v231, v53
	v_add_f32_e64 v52, v72, v52
	v_add_f32_e64 v53, v73, v53
	v_add_f32_e64 v52, v232, v52
	v_add_f32_e64 v53, v233, v53
	v_add_f32_e32 v52, v74, v52
	v_add_f32_e32 v53, v75, v53
	v_add_f32_e32 v52, v234, v52
	v_add_f32_e32 v53, v235, v53
	v_add_f32_e32 v52, v76, v52
	v_add_f32_e32 v53, v77, v53
	v_add_f32_e32 v52, v120, v52
	v_add_f32_e32 v53, v121, v53
	v_add_f32_e32 v52, v78, v52
	v_add_f32_e32 v53, v79, v53
	v_add_f32_e32 v52, v52, v53
	v_add_f32_e32 v214, v214, v52

.LBB0_1015:
	s_add_i32 s13, s2, -3
	s_waitcnt lgkmcnt(2)
	v_lshrrev_b32_e32 v48, s13, v128
	v_and_b32_e32 v48, 1, v48
	v_cmp_eq_u32_e64 s[14:15], 1, v48
	v_bfe_u32 v48, v128, s13, 1
	s_add_i32 s12, s1, s2
	v_cmp_ne_u32_e32 vcc, 0, v48
	s_cbranch_vccz .LBB0_1023
	s_cmp_eq_u32 s12, 3
	s_cbranch_scc1 .Lse_slow
	v_cndmask_b32_e64 v48, v210, 0, s[14:15]
	v_add_f32_e32 v62, v46, v48
	v_add_f32_e32 v63, v47, v48
	v_add_f32_e32 v60, v44, v48
	v_add_f32_e32 v61, v45, v48
	v_add_f32_e32 v58, v42, v48
	v_add_f32_e32 v59, v43, v48
	v_add_f32_e32 v56, v40, v48
	v_add_f32_e32 v57, v41, v48
	v_add_f32_e32 v54, v38, v48
	v_add_f32_e32 v55, v39, v48
	v_add_f32_e32 v52, v36, v48
	v_add_f32_e32 v53, v37, v48
	v_add_f32_e32 v50, v34, v48
	v_add_f32_e32 v51, v35, v48
	v_add_f32_e32 v49, v33, v48
	v_add_f32_e32 v48, v32, v48
	ds_read_b128 v[112:115], v131
	ds_read_b128 v[116:119], v131 offset:32
	s_waitcnt lgkmcnt(1)
	v_mfma_f32_32x32x16_bf16 v[64:79], v[112:115], v[80:83], v[48:63]
	ds_read_b128 v[112:115], v131 offset:4608
	ds_read_b128 v[120:123], v131 offset:4640
	s_waitcnt lgkmcnt(1)
	v_mfma_f32_32x32x16_bf16 v[48:63], v[112:115], v[80:83], v[48:63]
	v_mfma_f32_32x32x16_bf16 v[64:79], v[116:119], v[84:87], v[64:79]
	ds_read_b128 v[112:115], v131 offset:64
	ds_read_b128 v[116:119], v131 offset:96
	s_waitcnt lgkmcnt(2)
	v_mfma_f32_32x32x16_bf16 v[48:63], v[120:123], v[84:87], v[48:63]
	s_waitcnt lgkmcnt(1)
	v_mfma_f32_32x32x16_bf16 v[64:79], v[112:115], v[88:91], v[64:79]
	ds_read_b128 v[112:115], v131 offset:4672
	ds_read_b128 v[218:221], v131 offset:4704
	s_waitcnt lgkmcnt(1)
	v_mfma_f32_32x32x16_bf16 v[48:63], v[112:115], v[88:91], v[48:63]
	v_mfma_f32_32x32x16_bf16 v[64:79], v[116:119], v[92:95], v[64:79]
	ds_read_b64_tr_b16 v[120:121], v160 offset:18432
	ds_read_b64_tr_b16 v[122:123], v160 offset:19968
	ds_read_b64_tr_b16 v[114:115], v160 offset:20032
	ds_read_b64_tr_b16 v[112:113], v160 offset:18496
	ds_read_b64_tr_b16 v[124:125], v160 offset:21504
	ds_read_b64_tr_b16 v[126:127], v160 offset:23040
	ds_read_b64_tr_b16 v[118:119], v160 offset:23104
	ds_read_b64_tr_b16 v[116:117], v160 offset:21568
	s_waitcnt lgkmcnt(8)
	v_mfma_f32_32x32x16_bf16 v[48:63], v[218:221], v[92:95], v[48:63]
	s_branch .LBB0_1020
.Lse_slow:
	s_cmp_eq_u32 s12, 3
	s_cselect_b64 vcc, -1, 0
	v_cndmask_b32_e32 v216, 63, v193, vcc
	v_cmp_eq_u32_e32 vcc, 63, v216
	s_xor_b64 s[4:5], s[14:15], -1
	ds_read_b128 v[112:115], v131
	ds_read_b128 v[116:119], v131 offset:32
	s_or_b64 s[18:19], vcc, s[4:5]
	v_cndmask_b32_e64 v48, 0, 1, s[18:19]
	s_and_b64 s[16:17], vcc, s[14:15]
	v_cmp_ne_u32_e32 vcc, 0, v48
	s_cmp_lg_u64 vcc, exec
	s_cselect_b64 s[18:19], -1, 0
	s_or_b64 s[16:17], s[16:17], s[18:19]
	v_cndmask_b32_e64 v48, v210, 0, s[16:17]
	v_add_f32_e32 v62, v46, v48
	v_add_f32_e32 v63, v47, v48
	v_add_f32_e32 v60, v44, v48
	v_add_f32_e32 v61, v45, v48
	v_add_f32_e32 v58, v42, v48
	v_add_f32_e32 v59, v43, v48
	v_add_f32_e32 v56, v40, v48
	v_add_f32_e32 v57, v41, v48
	v_add_f32_e32 v54, v38, v48
	v_add_f32_e32 v55, v39, v48
	v_add_f32_e32 v52, v36, v48
	v_add_f32_e32 v53, v37, v48
	v_add_f32_e32 v50, v34, v48
	v_add_f32_e32 v51, v35, v48
	v_add_f32_e32 v49, v33, v48
	v_add_f32_e32 v48, v32, v48
	s_cmp_eq_u64 vcc, exec
	s_waitcnt lgkmcnt(1)
	v_mfma_f32_32x32x16_bf16 v[64:79], v[112:115], v[80:83], v[48:63]
	ds_read_b128 v[112:115], v131 offset:4608
	ds_read_b128 v[120:123], v131 offset:4640
	s_waitcnt lgkmcnt(1)
	v_mfma_f32_32x32x16_bf16 v[48:63], v[112:115], v[80:83], v[48:63]
	v_mfma_f32_32x32x16_bf16 v[64:79], v[116:119], v[84:87], v[64:79]
	ds_read_b128 v[112:115], v131 offset:64
	ds_read_b128 v[116:119], v131 offset:96
	s_waitcnt lgkmcnt(2)
	v_mfma_f32_32x32x16_bf16 v[48:63], v[120:123], v[84:87], v[48:63]
	s_waitcnt lgkmcnt(1)
	v_mfma_f32_32x32x16_bf16 v[64:79], v[112:115], v[88:91], v[64:79]
	ds_read_b128 v[112:115], v131 offset:4672
	ds_read_b128 v[218:221], v131 offset:4704
	s_waitcnt lgkmcnt(1)
	v_mfma_f32_32x32x16_bf16 v[48:63], v[112:115], v[88:91], v[48:63]
	v_mfma_f32_32x32x16_bf16 v[64:79], v[116:119], v[92:95], v[64:79]
	ds_read_b64_tr_b16 v[120:121], v160 offset:18432
	ds_read_b64_tr_b16 v[122:123], v160 offset:19968
	ds_read_b64_tr_b16 v[114:115], v160 offset:20032
	ds_read_b64_tr_b16 v[112:113], v160 offset:18496
	ds_read_b64_tr_b16 v[124:125], v160 offset:21504
	ds_read_b64_tr_b16 v[126:127], v160 offset:23040
	ds_read_b64_tr_b16 v[118:119], v160 offset:23104
	ds_read_b64_tr_b16 v[116:117], v160 offset:21568
	s_waitcnt lgkmcnt(8)
	v_mfma_f32_32x32x16_bf16 v[48:63], v[218:221], v[92:95], v[48:63]
	s_cbranch_scc1 .LBB0_1020
	v_cmp_le_u32_e64 s[16:17], v161, v216
	v_cmp_le_u32_e64 s[18:19], v162, v216
	v_cmp_le_u32_e64 s[20:21], v164, v216
	v_cmp_le_u32_e64 s[22:23], v166, v216
	v_cmp_le_u32_e64 s[24:25], v168, v216
	v_cmp_le_u32_e64 s[26:27], v170, v216
	v_cmp_le_u32_e64 s[28:29], v172, v216
	v_cmp_le_u32_e64 s[30:31], v174, v216
	v_cmp_le_u32_e64 s[34:35], v176, v216
	v_cmp_le_u32_e64 s[36:37], v178, v216
	v_cmp_le_u32_e64 s[38:39], v180, v216
	v_cmp_le_u32_e64 s[40:41], v182, v216
	v_cmp_le_u32_e64 s[42:43], v184, v216
	v_cmp_le_u32_e64 s[44:45], v186, v216
	v_cmp_le_u32_e64 s[46:47], v189, v216
	s_and_b64 s[16:17], s[14:15], s[16:17]
	s_and_b64 s[18:19], s[14:15], s[18:19]
	s_and_b64 s[20:21], s[14:15], s[20:21]
	s_and_b64 s[22:23], s[14:15], s[22:23]
	s_and_b64 s[24:25], s[14:15], s[24:25]
	s_and_b64 s[26:27], s[14:15], s[26:27]
	s_and_b64 s[28:29], s[14:15], s[28:29]
	s_and_b64 s[30:31], s[14:15], s[30:31]
	s_and_b64 s[34:35], s[14:15], s[34:35]
	s_and_b64 s[36:37], s[14:15], s[36:37]
	s_and_b64 s[38:39], s[14:15], s[38:39]
	s_and_b64 s[40:41], s[14:15], s[40:41]
	s_and_b64 s[42:43], s[14:15], s[42:43]
	s_and_b64 s[44:45], s[14:15], s[44:45]
	s_and_b64 s[46:47], s[14:15], s[46:47]
	v_cmp_gt_u32_e64 s[48:49], v191, v216
	v_cmp_le_u32_e32 vcc, v138, v216
	v_cndmask_b32_e64 v48, v210, v48, s[16:17]
	v_cmp_lt_u32_e64 s[16:17], v138, v216
	v_cndmask_b32_e64 v49, v210, v49, s[18:19]
	v_cmp_le_u32_e64 s[18:19], v163, v216
	v_cndmask_b32_e64 v50, v210, v50, s[20:21]
	v_cmp_le_u32_e64 s[20:21], v165, v216
	v_cndmask_b32_e64 v51, v210, v51, s[22:23]
	v_cmp_le_u32_e64 s[22:23], v167, v216
	v_cndmask_b32_e64 v52, v210, v52, s[24:25]
	v_cmp_le_u32_e64 s[24:25], v169, v216
	v_cndmask_b32_e64 v53, v210, v53, s[26:27]
	v_cmp_le_u32_e64 s[26:27], v171, v216
	v_cndmask_b32_e64 v54, v210, v54, s[28:29]
	v_cmp_le_u32_e64 s[28:29], v173, v216
	v_cndmask_b32_e64 v55, v210, v55, s[30:31]
	v_cmp_le_u32_e64 s[30:31], v175, v216
	v_cndmask_b32_e64 v56, v210, v56, s[34:35]
	v_cmp_le_u32_e64 s[34:35], v177, v216
	v_cndmask_b32_e64 v57, v210, v57, s[36:37]
	v_cmp_le_u32_e64 s[36:37], v179, v216
	v_cndmask_b32_e64 v58, v210, v58, s[38:39]
	v_cmp_le_u32_e64 s[38:39], v181, v216
	v_cndmask_b32_e64 v59, v210, v59, s[40:41]
	v_cmp_le_u32_e64 s[40:41], v183, v216
	v_cndmask_b32_e64 v60, v210, v60, s[42:43]
	v_cmp_le_u32_e64 s[42:43], v185, v216
	v_cndmask_b32_e64 v61, v210, v61, s[44:45]
	v_cmp_le_u32_e64 s[44:45], v187, v216
	v_cndmask_b32_e64 v62, v210, v62, s[46:47]
	v_cmp_le_u32_e64 s[46:47], v190, v216
	s_or_b64 s[48:49], s[4:5], s[48:49]
	s_and_saveexec_b64 s[4:5], s[48:49]
	v_mov_b32_e32 v63, s33
	s_or_b64 exec, exec, s[4:5]
	s_and_b64 vcc, s[14:15], vcc
	v_cndmask_b32_e32 v64, v210, v64, vcc
	s_and_b64 vcc, s[14:15], s[16:17]
	v_cndmask_b32_e32 v65, v210, v65, vcc
	s_and_b64 vcc, s[14:15], s[18:19]
	v_cndmask_b32_e32 v66, v210, v66, vcc
	s_and_b64 vcc, s[14:15], s[20:21]
	v_cndmask_b32_e32 v67, v210, v67, vcc
	s_and_b64 vcc, s[14:15], s[22:23]
	v_cndmask_b32_e32 v68, v210, v68, vcc
	s_and_b64 vcc, s[14:15], s[24:25]
	v_cndmask_b32_e32 v69, v210, v69, vcc
	s_and_b64 vcc, s[14:15], s[26:27]
	v_cndmask_b32_e32 v70, v210, v70, vcc
	s_and_b64 vcc, s[14:15], s[28:29]
	v_cndmask_b32_e32 v71, v210, v71, vcc
	s_and_b64 vcc, s[14:15], s[30:31]
	v_cndmask_b32_e32 v72, v210, v72, vcc
	s_and_b64 vcc, s[14:15], s[34:35]
	v_cndmask_b32_e32 v73, v210, v73, vcc
	s_and_b64 vcc, s[14:15], s[36:37]
	v_cndmask_b32_e32 v74, v210, v74, vcc
	s_and_b64 vcc, s[14:15], s[38:39]
	v_cndmask_b32_e32 v75, v210, v75, vcc
	s_and_b64 vcc, s[14:15], s[40:41]
	v_cndmask_b32_e32 v76, v210, v76, vcc
	s_and_b64 vcc, s[14:15], s[42:43]
	v_cndmask_b32_e32 v77, v210, v77, vcc
	s_and_b64 vcc, s[14:15], s[44:45]
	v_cndmask_b32_e32 v78, v210, v78, vcc
	s_and_b64 vcc, s[14:15], s[46:47]
	v_cndmask_b32_e32 v79, v210, v79, vcc

.LBB0_1022:
	v_exp_f32_e32 v217, v64
	v_exp_f32_e32 v216, v48
	v_exp_f32_e32 v219, v65
	v_exp_f32_e32 v218, v49
	v_exp_f32_e32 v221, v66
	v_exp_f32_e32 v220, v50
	v_exp_f32_e32 v223, v67
	v_exp_f32_e32 v227, v68
	v_exp_f32_e32 v69, v69
	v_exp_f32_e32 v229, v70
	v_exp_f32_e32 v71, v71
	v_mov_b32_e32 v48, v216
	v_mov_b32_e32 v49, v217
	v_exp_f32_e32 v222, v51
	v_add_f32_e32 v48, v218, v48
	v_add_f32_e32 v49, v219, v49
	v_cvt_pk_bf16_f32 v50, v227, v69
	v_add_f32_e32 v224, v220, v48
	v_add_f32_e32 v225, v221, v49
	v_cvt_pk_bf16_f32 v48, v217, v219
	v_cvt_pk_bf16_f32 v49, v221, v223
	v_cvt_pk_bf16_f32 v51, v229, v71
	v_exp_f32_e32 v231, v72
	v_exp_f32_e32 v73, v73
	s_waitcnt lgkmcnt(6)
	v_mfma_f32_32x32x16_bf16 v[16:31], v[120:123], v[48:51], v[16:31]
	v_exp_f32_e32 v233, v74
	v_exp_f32_e32 v75, v75
	v_exp_f32_e32 v235, v76
	v_exp_f32_e32 v77, v77
	v_exp_f32_e32 v121, v78
	v_exp_f32_e32 v79, v79
	v_cvt_pk_bf16_f32 v64, v231, v73
	s_waitcnt lgkmcnt(4)
	v_mfma_f32_32x32x16_bf16 v[0:15], v[112:115], v[48:51], v[0:15]
	v_cvt_pk_bf16_f32 v65, v233, v75
	v_cvt_pk_bf16_f32 v66, v235, v77
	v_cvt_pk_bf16_f32 v67, v121, v79
	v_exp_f32_e32 v226, v52
	v_exp_f32_e32 v68, v53
	v_exp_f32_e32 v228, v54
	v_exp_f32_e32 v70, v55
	s_waitcnt lgkmcnt(2)
	v_mfma_f32_32x32x16_bf16 v[16:31], v[124:127], v[64:67], v[16:31]
	ds_read_b64_tr_b16 v[48:49], v160 offset:24576
	ds_read_b64_tr_b16 v[50:51], v160 offset:26112
	v_exp_f32_e32 v230, v56
	v_exp_f32_e32 v72, v57
	v_exp_f32_e32 v232, v58
	v_exp_f32_e32 v74, v59
	ds_read_b64_tr_b16 v[52:53], v160 offset:27648
	ds_read_b64_tr_b16 v[54:55], v160 offset:29184
	ds_read_b64_tr_b16 v[58:59], v160 offset:26176
	ds_read_b64_tr_b16 v[56:57], v160 offset:24640
	v_exp_f32_e32 v234, v60
	s_waitcnt lgkmcnt(6)
	v_mfma_f32_32x32x16_bf16 v[0:15], v[116:119], v[64:67], v[0:15]
	v_cvt_pk_bf16_f32 v64, v216, v218
	v_cvt_pk_bf16_f32 v65, v220, v222
	v_cvt_pk_bf16_f32 v66, v226, v68
	v_cvt_pk_bf16_f32 v67, v228, v70
	v_exp_f32_e32 v76, v61
	v_exp_f32_e32 v120, v62
	v_exp_f32_e32 v78, v63
	s_waitcnt lgkmcnt(4)
	v_mfma_f32_32x32x16_bf16 v[16:31], v[48:51], v[64:67], v[16:31]
	v_add_f32_e64 v122, v222, v224
	v_add_f32_e64 v123, v223, v225
	v_cvt_pk_bf16_f32 v60, v230, v72
	v_cvt_pk_bf16_f32 v61, v232, v74
	v_cvt_pk_bf16_f32 v62, v234, v76
	v_cvt_pk_bf16_f32 v63, v120, v78
	ds_read_b64_tr_b16 v[50:51], v160 offset:29248
	ds_read_b64_tr_b16 v[48:49], v160 offset:27712
	s_waitcnt lgkmcnt(2)
	v_mfma_f32_32x32x16_bf16 v[0:15], v[56:59], v[64:67], v[0:15]
	v_mfma_f32_32x32x16_bf16 v[16:31], v[52:55], v[60:63], v[16:31]
	v_add_f32_e64 v52, v226, v122
	v_add_f32_e64 v53, v227, v123
	v_add_f32_e64 v52, v68, v52
	v_add_f32_e64 v53, v69, v53
	v_add_f32_e64 v52, v228, v52
	v_add_f32_e64 v53, v229, v53
	v_add_f32_e32 v52, v70, v52
	v_add_f32_e32 v53, v71, v53
	s_waitcnt lgkmcnt(0)
	v_mfma_f32_32x32x16_bf16 v[0:15], v[48:51], v[60:63], v[0:15]
	v_add_f32_e64 v52, v230, v52
	v_add_f32_e64 v53, v231, v53
	v_add_f32_e64 v52, v72, v52
	v_add_f32_e64 v53, v73, v53
	v_add_f32_e64 v52, v232, v52
	v_add_f32_e64 v53, v233, v53
	v_add_f32_e32 v52, v74, v52
	v_add_f32_e32 v53, v75, v53
	v_add_f32_e32 v52, v234, v52
	v_add_f32_e32 v53, v235, v53
	v_add_f32_e32 v52, v76, v52
	v_add_f32_e32 v53, v77, v53
	v_add_f32_e32 v52, v120, v52
	v_add_f32_e32 v53, v121, v53
	v_add_f32_e32 v52, v78, v52
	v_add_f32_e32 v53, v79, v53
	v_add_f32_e32 v52, v52, v53
	v_add_f32_e32 v214, v214, v52

.LBB0_1026:
	s_add_i32 s4, s2, -2
	v_lshrrev_b32_e32 v48, s4, v128
	v_and_b32_e32 v48, 1, v48
	v_cmp_eq_u32_e64 s[14:15], 1, v48
	v_bfe_u32 v48, v128, s4, 1
	v_cmp_ne_u32_e32 vcc, 0, v48
	s_cbranch_vccz .LBB0_1012
	s_cmp_eq_u32 s12, 2
	s_cbranch_scc1 .Lso_slow
	v_cndmask_b32_e64 v48, v210, 0, s[14:15]
	v_add_f32_e32 v62, v46, v48
	v_add_f32_e32 v63, v47, v48
	v_add_f32_e32 v60, v44, v48
	v_add_f32_e32 v61, v45, v48
	v_add_f32_e32 v58, v42, v48
	v_add_f32_e32 v59, v43, v48
	v_add_f32_e32 v56, v40, v48
	v_add_f32_e32 v57, v41, v48
	v_add_f32_e32 v54, v38, v48
	v_add_f32_e32 v55, v39, v48
	v_add_f32_e32 v52, v36, v48
	v_add_f32_e32 v53, v37, v48
	v_add_f32_e32 v50, v34, v48
	v_add_f32_e32 v51, v35, v48
	v_add_f32_e32 v49, v33, v48
	v_add_f32_e32 v48, v32, v48
	ds_read_b128 v[112:115], v131 offset:9216
	ds_read_b128 v[116:119], v131 offset:9248
	s_waitcnt lgkmcnt(1)
	v_mfma_f32_32x32x16_bf16 v[64:79], v[112:115], v[80:83], v[48:63]
	ds_read_b128 v[112:115], v131 offset:13824
	ds_read_b128 v[120:123], v131 offset:13856
	s_waitcnt lgkmcnt(1)
	v_mfma_f32_32x32x16_bf16 v[48:63], v[112:115], v[80:83], v[48:63]
	v_mfma_f32_32x32x16_bf16 v[64:79], v[116:119], v[84:87], v[64:79]
	ds_read_b128 v[112:115], v131 offset:9280
	ds_read_b128 v[116:119], v131 offset:9312
	s_waitcnt lgkmcnt(2)
	v_mfma_f32_32x32x16_bf16 v[48:63], v[120:123], v[84:87], v[48:63]
	s_waitcnt lgkmcnt(1)
	v_mfma_f32_32x32x16_bf16 v[64:79], v[112:115], v[88:91], v[64:79]
	ds_read_b128 v[112:115], v131 offset:13888
	ds_read_b128 v[218:221], v131 offset:13920
	s_waitcnt lgkmcnt(1)
	v_mfma_f32_32x32x16_bf16 v[48:63], v[112:115], v[88:91], v[48:63]
	v_mfma_f32_32x32x16_bf16 v[64:79], v[116:119], v[92:95], v[64:79]
	ds_read_b64_tr_b16 v[120:121], v160 offset:30720
	ds_read_b64_tr_b16 v[122:123], v160 offset:32256
	ds_read_b64_tr_b16 v[114:115], v160 offset:32320
	ds_read_b64_tr_b16 v[112:113], v160 offset:30784
	ds_read_b64_tr_b16 v[124:125], v160 offset:33792
	ds_read_b64_tr_b16 v[126:127], v160 offset:35328
	ds_read_b64_tr_b16 v[118:119], v160 offset:35392
	ds_read_b64_tr_b16 v[116:117], v160 offset:33856
	s_waitcnt lgkmcnt(8)
	v_mfma_f32_32x32x16_bf16 v[48:63], v[218:221], v[92:95], v[48:63]
	s_branch .LBB0_1031
.Lso_slow:
	s_cmp_eq_u32 s12, 2
	s_cselect_b64 vcc, -1, 0
	v_cndmask_b32_e32 v216, 63, v193, vcc
	v_cmp_eq_u32_e32 vcc, 63, v216
	s_xor_b64 s[4:5], s[14:15], -1
	ds_read_b128 v[112:115], v131 offset:9216
	ds_read_b128 v[116:119], v131 offset:9248
	s_or_b64 s[16:17], vcc, s[4:5]
	v_cndmask_b32_e64 v48, 0, 1, s[16:17]
	s_and_b64 s[12:13], vcc, s[14:15]
	v_cmp_ne_u32_e32 vcc, 0, v48
	s_cmp_lg_u64 vcc, exec
	s_cselect_b64 s[16:17], -1, 0
	s_or_b64 s[12:13], s[12:13], s[16:17]
	v_cndmask_b32_e64 v48, v210, 0, s[12:13]
	v_add_f32_e32 v62, v46, v48
	v_add_f32_e32 v63, v47, v48
	v_add_f32_e32 v60, v44, v48
	v_add_f32_e32 v61, v45, v48
	v_add_f32_e32 v58, v42, v48
	v_add_f32_e32 v59, v43, v48
	v_add_f32_e32 v56, v40, v48
	v_add_f32_e32 v57, v41, v48
	v_add_f32_e32 v54, v38, v48
	v_add_f32_e32 v55, v39, v48
	v_add_f32_e32 v52, v36, v48
	v_add_f32_e32 v53, v37, v48
	v_add_f32_e32 v50, v34, v48
	v_add_f32_e32 v51, v35, v48
	v_add_f32_e32 v49, v33, v48
	v_add_f32_e32 v48, v32, v48
	s_cmp_eq_u64 vcc, exec
	s_waitcnt lgkmcnt(1)
	v_mfma_f32_32x32x16_bf16 v[64:79], v[112:115], v[80:83], v[48:63]
	ds_read_b128 v[112:115], v131 offset:13824
	ds_read_b128 v[120:123], v131 offset:13856
	s_waitcnt lgkmcnt(1)
	v_mfma_f32_32x32x16_bf16 v[48:63], v[112:115], v[80:83], v[48:63]
	v_mfma_f32_32x32x16_bf16 v[64:79], v[116:119], v[84:87], v[64:79]
	ds_read_b128 v[112:115], v131 offset:9280
	ds_read_b128 v[116:119], v131 offset:9312
	s_waitcnt lgkmcnt(2)
	v_mfma_f32_32x32x16_bf16 v[48:63], v[120:123], v[84:87], v[48:63]
	s_waitcnt lgkmcnt(1)
	v_mfma_f32_32x32x16_bf16 v[64:79], v[112:115], v[88:91], v[64:79]
	ds_read_b128 v[112:115], v131 offset:13888
	ds_read_b128 v[218:221], v131 offset:13920
	s_waitcnt lgkmcnt(1)
	v_mfma_f32_32x32x16_bf16 v[48:63], v[112:115], v[88:91], v[48:63]
	v_mfma_f32_32x32x16_bf16 v[64:79], v[116:119], v[92:95], v[64:79]
	ds_read_b64_tr_b16 v[120:121], v160 offset:30720
	ds_read_b64_tr_b16 v[122:123], v160 offset:32256
	ds_read_b64_tr_b16 v[114:115], v160 offset:32320
	ds_read_b64_tr_b16 v[112:113], v160 offset:30784
	ds_read_b64_tr_b16 v[124:125], v160 offset:33792
	ds_read_b64_tr_b16 v[126:127], v160 offset:35328
	ds_read_b64_tr_b16 v[118:119], v160 offset:35392
	ds_read_b64_tr_b16 v[116:117], v160 offset:33856
	s_waitcnt lgkmcnt(8)
	v_mfma_f32_32x32x16_bf16 v[48:63], v[218:221], v[92:95], v[48:63]
	s_cbranch_scc1 .LBB0_1031
	v_cmp_le_u32_e64 s[16:17], v161, v216
	v_cmp_le_u32_e64 s[18:19], v162, v216
	v_cmp_le_u32_e64 s[20:21], v164, v216
	v_cmp_le_u32_e64 s[22:23], v166, v216
	v_cmp_le_u32_e64 s[24:25], v168, v216
	v_cmp_le_u32_e64 s[26:27], v170, v216
	v_cmp_le_u32_e64 s[28:29], v172, v216
	v_cmp_le_u32_e64 s[30:31], v174, v216
	v_cmp_le_u32_e64 s[34:35], v176, v216
	v_cmp_le_u32_e64 s[36:37], v178, v216
	v_cmp_le_u32_e64 s[38:39], v180, v216
	v_cmp_le_u32_e64 s[40:41], v182, v216
	v_cmp_le_u32_e64 s[42:43], v184, v216
	v_cmp_le_u32_e64 s[44:45], v186, v216
	v_cmp_le_u32_e64 s[46:47], v189, v216
	s_and_b64 s[16:17], s[14:15], s[16:17]
	s_and_b64 s[18:19], s[14:15], s[18:19]
	s_and_b64 s[20:21], s[14:15], s[20:21]
	s_and_b64 s[22:23], s[14:15], s[22:23]
	s_and_b64 s[24:25], s[14:15], s[24:25]
	s_and_b64 s[26:27], s[14:15], s[26:27]
	s_and_b64 s[28:29], s[14:15], s[28:29]
	s_and_b64 s[30:31], s[14:15], s[30:31]
	s_and_b64 s[34:35], s[14:15], s[34:35]
	s_and_b64 s[36:37], s[14:15], s[36:37]
	s_and_b64 s[38:39], s[14:15], s[38:39]
	s_and_b64 s[40:41], s[14:15], s[40:41]
	s_and_b64 s[42:43], s[14:15], s[42:43]
	s_and_b64 s[44:45], s[14:15], s[44:45]
	s_and_b64 s[46:47], s[14:15], s[46:47]
	v_cmp_gt_u32_e64 s[48:49], v191, v216
	v_cmp_le_u32_e32 vcc, v138, v216
	v_cndmask_b32_e64 v48, v210, v48, s[16:17]
	v_cmp_lt_u32_e64 s[16:17], v138, v216
	v_cndmask_b32_e64 v49, v210, v49, s[18:19]
	v_cmp_le_u32_e64 s[18:19], v163, v216
	v_cndmask_b32_e64 v50, v210, v50, s[20:21]
	v_cmp_le_u32_e64 s[20:21], v165, v216
	v_cndmask_b32_e64 v51, v210, v51, s[22:23]
	v_cmp_le_u32_e64 s[22:23], v167, v216
	v_cndmask_b32_e64 v52, v210, v52, s[24:25]
	v_cmp_le_u32_e64 s[24:25], v169, v216
	v_cndmask_b32_e64 v53, v210, v53, s[26:27]
	v_cmp_le_u32_e64 s[26:27], v171, v216
	v_cndmask_b32_e64 v54, v210, v54, s[28:29]
	v_cmp_le_u32_e64 s[28:29], v173, v216
	v_cndmask_b32_e64 v55, v210, v55, s[30:31]
	v_cmp_le_u32_e64 s[30:31], v175, v216
	v_cndmask_b32_e64 v56, v210, v56, s[34:35]
	v_cmp_le_u32_e64 s[34:35], v177, v216
	v_cndmask_b32_e64 v57, v210, v57, s[36:37]
	v_cmp_le_u32_e64 s[36:37], v179, v216
	v_cndmask_b32_e64 v58, v210, v58, s[38:39]
	v_cmp_le_u32_e64 s[38:39], v181, v216
	v_cndmask_b32_e64 v59, v210, v59, s[40:41]
	v_cmp_le_u32_e64 s[40:41], v183, v216
	v_cndmask_b32_e64 v60, v210, v60, s[42:43]
	v_cmp_le_u32_e64 s[42:43], v185, v216
	v_cndmask_b32_e64 v61, v210, v61, s[44:45]
	v_cmp_le_u32_e64 s[44:45], v187, v216
	v_cndmask_b32_e64 v62, v210, v62, s[46:47]
	v_cmp_le_u32_e64 s[46:47], v190, v216
	s_or_b64 s[12:13], s[4:5], s[48:49]
	s_and_saveexec_b64 s[4:5], s[12:13]
	v_mov_b32_e32 v63, s33
	s_or_b64 exec, exec, s[4:5]
	s_and_b64 vcc, s[14:15], vcc
	v_cndmask_b32_e32 v64, v210, v64, vcc
	s_and_b64 vcc, s[14:15], s[16:17]
	v_cndmask_b32_e32 v65, v210, v65, vcc
	s_and_b64 vcc, s[14:15], s[18:19]
	v_cndmask_b32_e32 v66, v210, v66, vcc
	s_and_b64 vcc, s[14:15], s[20:21]
	v_cndmask_b32_e32 v67, v210, v67, vcc
	s_and_b64 vcc, s[14:15], s[22:23]
	v_cndmask_b32_e32 v68, v210, v68, vcc
	s_and_b64 vcc, s[14:15], s[24:25]
	v_cndmask_b32_e32 v69, v210, v69, vcc
	s_and_b64 vcc, s[14:15], s[26:27]
	v_cndmask_b32_e32 v70, v210, v70, vcc
	s_and_b64 vcc, s[14:15], s[28:29]
	v_cndmask_b32_e32 v71, v210, v71, vcc
	s_and_b64 vcc, s[14:15], s[30:31]
	v_cndmask_b32_e32 v72, v210, v72, vcc
	s_and_b64 vcc, s[14:15], s[34:35]
	v_cndmask_b32_e32 v73, v210, v73, vcc
	s_and_b64 vcc, s[14:15], s[36:37]
	v_cndmask_b32_e32 v74, v210, v74, vcc
	s_and_b64 vcc, s[14:15], s[38:39]
	v_cndmask_b32_e32 v75, v210, v75, vcc
	s_and_b64 vcc, s[14:15], s[40:41]
	v_cndmask_b32_e32 v76, v210, v76, vcc
	s_and_b64 vcc, s[14:15], s[42:43]
	v_cndmask_b32_e32 v77, v210, v77, vcc
	s_and_b64 vcc, s[14:15], s[44:45]
	v_cndmask_b32_e32 v78, v210, v78, vcc
	s_and_b64 vcc, s[14:15], s[46:47]
	v_cndmask_b32_e32 v79, v210, v79, vcc

.Lwe_slow:
	s_cmp_lg_u32 s3, s13
	s_cselect_b64 s[4:5], -1, 0
	s_cmp_eq_u32 s1, s13
	s_cselect_b64 vcc, -1, 0
	v_cndmask_b32_e64 v216, v205, 0, s[4:5]
	v_cndmask_b32_e32 v217, 63, v193, vcc
	v_cmp_le_u32_e32 vcc, v216, v217
	v_cmp_gt_u32_e64 s[14:15], 64, v216
	s_and_b64 vcc, s[14:15], vcc
	s_cbranch_vccz .LBB0_1109
	v_cmp_eq_u32_e64 s[14:15], 63, v217
	s_and_b64 s[16:17], s[4:5], s[14:15]
	s_xor_b64 s[4:5], vcc, -1
	ds_read_b128 v[112:115], v131
	ds_read_b128 v[116:119], v131 offset:32
	s_or_b64 s[14:15], s[16:17], s[4:5]
	v_cndmask_b32_e64 v48, 0, 1, s[14:15]
	v_cmp_ne_u32_e64 s[14:15], 0, v48
	s_cmp_lg_u64 s[14:15], exec
	s_cselect_b64 s[18:19], -1, 0
	s_or_b64 s[16:17], s[16:17], s[18:19]
	v_cndmask_b32_e64 v48, v210, 0, s[16:17]
	v_add_f32_e32 v62, v46, v48
	v_add_f32_e32 v63, v47, v48
	v_add_f32_e32 v60, v44, v48
	v_add_f32_e32 v61, v45, v48
	v_add_f32_e32 v58, v42, v48
	v_add_f32_e32 v59, v43, v48
	v_add_f32_e32 v56, v40, v48
	v_add_f32_e32 v57, v41, v48
	v_add_f32_e32 v54, v38, v48
	v_add_f32_e32 v55, v39, v48
	v_add_f32_e32 v52, v36, v48
	v_add_f32_e32 v53, v37, v48
	v_add_f32_e32 v50, v34, v48
	v_add_f32_e32 v51, v35, v48
	v_add_f32_e32 v49, v33, v48
	v_add_f32_e32 v48, v32, v48
	s_cmp_eq_u64 s[14:15], exec
	s_waitcnt lgkmcnt(1)
	v_mfma_f32_32x32x16_bf16 v[64:79], v[112:115], v[80:83], v[48:63]
	ds_read_b128 v[112:115], v131 offset:4608
	ds_read_b128 v[120:123], v131 offset:4640
	s_waitcnt lgkmcnt(1)
	v_mfma_f32_32x32x16_bf16 v[48:63], v[112:115], v[80:83], v[48:63]
	v_mfma_f32_32x32x16_bf16 v[64:79], v[116:119], v[84:87], v[64:79]
	ds_read_b128 v[112:115], v131 offset:64
	ds_read_b128 v[116:119], v131 offset:96
	s_waitcnt lgkmcnt(2)
	v_mfma_f32_32x32x16_bf16 v[48:63], v[120:123], v[84:87], v[48:63]
	s_waitcnt lgkmcnt(1)
	v_mfma_f32_32x32x16_bf16 v[64:79], v[112:115], v[88:91], v[64:79]
	ds_read_b128 v[112:115], v131 offset:4672
	ds_read_b128 v[218:221], v131 offset:4704
	s_waitcnt lgkmcnt(1)
	v_mfma_f32_32x32x16_bf16 v[48:63], v[112:115], v[88:91], v[48:63]
	v_mfma_f32_32x32x16_bf16 v[64:79], v[116:119], v[92:95], v[64:79]
	ds_read_b64_tr_b16 v[120:121], v160 offset:18432
	ds_read_b64_tr_b16 v[122:123], v160 offset:19968
	ds_read_b64_tr_b16 v[114:115], v160 offset:20032
	ds_read_b64_tr_b16 v[112:113], v160 offset:18496
	ds_read_b64_tr_b16 v[124:125], v160 offset:21504
	ds_read_b64_tr_b16 v[126:127], v160 offset:23040
	ds_read_b64_tr_b16 v[118:119], v160 offset:23104
	ds_read_b64_tr_b16 v[116:117], v160 offset:21568
	s_waitcnt lgkmcnt(8)
	v_mfma_f32_32x32x16_bf16 v[48:63], v[218:221], v[92:95], v[48:63]
	s_cbranch_scc1 .LBB0_1106
	s_mov_b64 s[14:15], s[4:5]
	s_and_saveexec_b64 s[18:19], vcc
	s_cbranch_execz .LBB0_1071
	v_cmp_lt_u32_e64 s[14:15], v161, v216
	v_cmp_gt_u32_e64 s[16:17], v161, v217
	s_or_b64 s[14:15], s[14:15], s[16:17]
	s_andn2_b64 s[16:17], s[4:5], exec
	s_and_b64 s[14:15], s[14:15], exec
	s_or_b64 s[14:15], s[16:17], s[14:15]
	s_or_b64 exec, exec, s[18:19]
	s_and_saveexec_b64 s[16:17], s[14:15]
	s_cbranch_execnz .LBB0_1072

.Lwo_slow:
	s_cmp_lg_u32 s2, s13
	s_cselect_b64 s[4:5], -1, 0
	s_cmp_eq_u32 s91, s13
	s_cselect_b64 vcc, -1, 0
	v_cndmask_b32_e64 v216, v205, 0, s[4:5]
	v_cndmask_b32_e32 v217, 63, v193, vcc
	v_cmp_le_u32_e32 vcc, v216, v217
	v_cmp_gt_u32_e64 s[14:15], 64, v216
	s_and_b64 vcc, s[14:15], vcc
	s_cbranch_vccz .LBB0_1182
	v_cmp_eq_u32_e64 s[14:15], 63, v217
	s_and_b64 s[16:17], s[4:5], s[14:15]
	s_xor_b64 s[4:5], vcc, -1
	ds_read_b128 v[112:115], v131 offset:9216
	ds_read_b128 v[116:119], v131 offset:9248
	s_or_b64 s[14:15], s[16:17], s[4:5]
	v_cndmask_b32_e64 v48, 0, 1, s[14:15]
	v_cmp_ne_u32_e64 s[14:15], 0, v48
	s_cmp_lg_u64 s[14:15], exec
	s_cselect_b64 s[18:19], -1, 0
	s_or_b64 s[16:17], s[16:17], s[18:19]
	v_cndmask_b32_e64 v48, v210, 0, s[16:17]
	v_add_f32_e32 v62, v46, v48
	v_add_f32_e32 v63, v47, v48
	v_add_f32_e32 v60, v44, v48
	v_add_f32_e32 v61, v45, v48
	v_add_f32_e32 v58, v42, v48
	v_add_f32_e32 v59, v43, v48
	v_add_f32_e32 v56, v40, v48
	v_add_f32_e32 v57, v41, v48
	v_add_f32_e32 v54, v38, v48
	v_add_f32_e32 v55, v39, v48
	v_add_f32_e32 v52, v36, v48
	v_add_f32_e32 v53, v37, v48
	v_add_f32_e32 v50, v34, v48
	v_add_f32_e32 v51, v35, v48
	v_add_f32_e32 v49, v33, v48
	v_add_f32_e32 v48, v32, v48
	s_cmp_eq_u64 s[14:15], exec
	s_waitcnt lgkmcnt(1)
	v_mfma_f32_32x32x16_bf16 v[64:79], v[112:115], v[80:83], v[48:63]
	ds_read_b128 v[112:115], v131 offset:13824
	ds_read_b128 v[120:123], v131 offset:13856
	s_waitcnt lgkmcnt(1)
	v_mfma_f32_32x32x16_bf16 v[48:63], v[112:115], v[80:83], v[48:63]
	v_mfma_f32_32x32x16_bf16 v[64:79], v[116:119], v[84:87], v[64:79]
	ds_read_b128 v[112:115], v131 offset:9280
	ds_read_b128 v[116:119], v131 offset:9312
	s_waitcnt lgkmcnt(2)
	v_mfma_f32_32x32x16_bf16 v[48:63], v[120:123], v[84:87], v[48:63]
	s_waitcnt lgkmcnt(1)
	v_mfma_f32_32x32x16_bf16 v[64:79], v[112:115], v[88:91], v[64:79]
	ds_read_b128 v[112:115], v131 offset:13888
	ds_read_b128 v[218:221], v131 offset:13920
	s_waitcnt lgkmcnt(1)
	v_mfma_f32_32x32x16_bf16 v[48:63], v[112:115], v[88:91], v[48:63]
	v_mfma_f32_32x32x16_bf16 v[64:79], v[116:119], v[92:95], v[64:79]
	ds_read_b64_tr_b16 v[120:121], v160 offset:30720
	ds_read_b64_tr_b16 v[122:123], v160 offset:32256
	ds_read_b64_tr_b16 v[114:115], v160 offset:32320
	ds_read_b64_tr_b16 v[112:113], v160 offset:30784
	ds_read_b64_tr_b16 v[124:125], v160 offset:33792
	ds_read_b64_tr_b16 v[126:127], v160 offset:35328
	ds_read_b64_tr_b16 v[118:119], v160 offset:35392
	ds_read_b64_tr_b16 v[116:117], v160 offset:33856
	s_waitcnt lgkmcnt(8)
	v_mfma_f32_32x32x16_bf16 v[48:63], v[218:221], v[92:95], v[48:63]
	s_cbranch_scc1 .LBB0_1179
	s_mov_b64 s[14:15], s[4:5]
	s_and_saveexec_b64 s[18:19], vcc
	s_cbranch_execz .LBB0_1144
	v_cmp_lt_u32_e64 s[14:15], v161, v216
	v_cmp_gt_u32_e64 s[16:17], v161, v217
	s_or_b64 s[14:15], s[14:15], s[16:17]
	s_andn2_b64 s[16:17], s[4:5], exec
	s_and_b64 s[14:15], s[14:15], exec
	s_or_b64 s[14:15], s[16:17], s[14:15]
	s_or_b64 exec, exec, s[18:19]
	s_and_saveexec_b64 s[16:17], s[14:15]
	s_cbranch_execnz .LBB0_1145
